# remove a barrier: skip the redundant grid barrier after the last step (exit directly), on top of v021
# baseline (speedup 1.0000x reference)
; #define LAS __attribute__((address_space(3)))
; DI unsigned xb_xcc_id() { return (unsigned)__builtin_amdgcn_s_getreg((3 << 11) | 20) & 0xFu; }
; #define GSYNC() do { unsigned char* wsb_ = p.ws; asm volatile("" : "+s"(wsb_)); xcd_barrier((unsigned*)(wsb_ + OFF_BAR), xst); } while (0)
; DI void xcd_barrier(unsigned* bar, volatile LAS unsigned* st) {
;   asm volatile("s_waitcnt vmcnt(0)" ::: "memory");
;   __syncthreads();
;   if (threadIdx.x == 0) {
;     const unsigned x = xb_xcc_id();
;     __builtin_amdgcn_s_waitcnt(0);
;     unsigned nloc = st[0], nx = st[1];
;     if (nloc == 0u) { xcd_barrier_complete(bar, x, nloc, nx); st[0] = nloc; st[1] = nx; }
; __global__ void __launch_bounds__(512, 2) mega(Params p) {
;     ...
;     GSYNC();
.LBB0_833:
	s_cmp_eq_u32 s57, 11
	s_cbranch_scc1 .LBB0_876
	v_readlane_b32 s0, v253, 0
	v_readlane_b32 s6, v253, 6
	v_readlane_b32 s7, v253, 7
	s_mov_b64 s[40:41], s[6:7]
	s_waitcnt vmcnt(0)
	v_readlane_b32 s1, v253, 1
	v_readlane_b32 s2, v253, 2
	v_readlane_b32 s3, v253, 3
	v_readlane_b32 s4, v253, 4
	v_readlane_b32 s5, v253, 5
	s_waitcnt vmcnt(0) lgkmcnt(0)
	s_barrier
	s_mov_b64 s[38:39], exec
	v_readlane_b32 s0, v253, 8
	v_readlane_b32 s1, v253, 9
	s_and_b64 s[0:1], s[38:39], s[0:1]
	s_mov_b64 exec, s[0:1]
	s_cbranch_execz .LBB0_321
	v_readlane_b32 s1, v254, 49
	s_getreg_b32 s0, hwreg(HW_REG_XCC_ID, 0, 4)
	s_waitcnt vmcnt(0) expcnt(0) lgkmcnt(0)
	v_mov_b32_e32 v0, s1
	ds_read_b32 v2, v0
	v_readlane_b32 s1, v254, 50
	s_and_b32 s2, s0, 15
	s_waitcnt lgkmcnt(0)
	v_cmp_ne_u32_e32 vcc, 0, v2
	v_mov_b32_e32 v0, s1
	ds_read_b32 v0, v0
	s_cbranch_vccnz .LBB0_848
	s_add_u32 s0, s40, 0x22f20200
	s_addc_u32 s1, s41, 0
	s_add_u32 s4, s40, 0x22f20400
	s_addc_u32 s5, s41, 0
	s_add_u32 s6, s40, 0x22f20500
	s_addc_u32 s7, s41, 0
	s_add_u32 s8, s40, 0x22f20600
	s_addc_u32 s9, s41, 0
	s_add_u32 s10, s40, 0x22f20700
	s_addc_u32 s11, s41, 0
	s_add_u32 s12, s40, 0x22f20800
	s_addc_u32 s13, s41, 0
	s_add_u32 s16, s40, 0x22f20900
	s_addc_u32 s17, s41, 0
	s_add_u32 s18, s40, 0x22f20a00
	s_addc_u32 s19, s41, 0
	s_add_u32 s20, s40, 0x22f20b00
	s_addc_u32 s21, s41, 0
	s_add_u32 s22, s40, 0x22f20c00
	s_addc_u32 s23, s41, 0
	s_add_u32 s24, s40, 0x22f20d00
	s_addc_u32 s25, s41, 0
	s_add_u32 s26, s40, 0x22f20e00
	s_addc_u32 s27, s41, 0
	s_add_u32 s28, s40, 0x22f20f00
	s_addc_u32 s29, s41, 0
	s_add_u32 s30, s40, 0x22f21000
	s_addc_u32 s31, s41, 0
	s_add_u32 s34, s40, 0x22f21100
	s_addc_u32 s35, s41, 0
	s_add_u32 s42, s40, 0x22f21200
	s_addc_u32 s43, s41, 0
	s_add_u32 s46, s40, 0x22f21300
	s_addc_u32 s47, s41, 0
	s_mov_b32 s3, 1
	s_mov_b64 s[58:59], 0
	s_branch .LBB0_838
